# GEMM prologues: second batch of tile DMAs issued before waiting on the first (one first-touch latency instead of two) in all 10 GEMM instances
# baseline (speedup 1.0000x reference)
.LBB0_35:
	v_readlane_b32 s36, v252, 58
	s_lshl_b32 s7, s7, 5
	v_mov_b32_e32 v1, v181
	v_readlane_b32 s37, v252, 59
	s_and_b32 s7, s7, 0x60
	s_add_i32 m0, s51, 0x18000
	v_lshl_add_u64 v[8:9], v[22:23], 0, s[94:95]
	v_lshl_add_u64 v[4:5], s[36:37], 0, v[0:1]
	v_mov_b32_e32 v133, v181
	s_lshl_b32 s15, s6, 13
	s_lshl_b32 s16, s7, 7
	s_nop 0
	s_nop 0
	global_load_lds_dwordx4 v[8:9], off
	v_lshl_add_u64 v[8:9], v[20:21], 0, s[94:95]
	s_add_i32 m0, s51, 0x1a000
	s_add_i32 s55, s51, 0x8000
	s_add_i32 s58, s51, 0xa000
	v_lshl_add_u64 v[6:7], s[36:37], 0, v[132:133]
	global_load_lds_dwordx4 v[8:9], off
	v_lshl_add_u64 v[4:5], v[4:5], 0, s[94:95]
	s_mov_b32 m0, s55
	s_add_u32 s10, s44, 0x40080
	global_load_lds_dwordx4 v[4:5], off
	v_lshl_add_u64 v[4:5], v[6:7], 0, s[94:95]
	s_mov_b32 m0, s58
	s_addc_u32 s11, s45, 0
	global_load_lds_dwordx4 v[4:5], off
	s_add_i32 m0, s51, 0x1c000
	v_lshl_add_u64 v[4:5], s[10:11], 0, v[180:181]
	global_load_lds_dwordx4 v[4:5], off
	v_lshl_add_u64 v[4:5], s[10:11], 0, v[134:135]
	s_add_i32 m0, s51, 0x1e000
	v_mov_b32_e32 v137, v181
	global_load_lds_dwordx4 v[4:5], off
	s_waitcnt vmcnt(8)
	s_barrier
	v_and_b32_e32 v4, 15, v24
	v_lshrrev_b32_e32 v5, 1, v24
	v_lshl_or_b32 v3, s6, 6, v4
	v_and_b32_e32 v5, 24, v5
	s_lshl_b32 s6, s6, 8
	v_lshlrev_b32_e32 v6, 1, v5
	s_add_i32 s6, s6, 0
	v_lshl_or_b32 v6, v4, 6, v6
	v_lshlrev_b32_e32 v4, 2, v4
	s_add_i32 s6, s6, 0x22000
	v_and_b32_e32 v7, 32, v4
	v_add_u32_e32 v143, s6, v4
	v_lshlrev_b32_e32 v4, 14, v25
	v_and_b32_e32 v4, 0xffff8000, v4
	v_or_b32_e32 v144, s7, v5
	v_lshl_add_u32 v4, v26, 11, v4
	v_and_b32_e32 v5, 1, v25
	v_lshl_or_b32 v4, v5, 6, v4
	v_lshl_add_u32 v136, v27, 1, v4
	v_lshlrev_b32_e32 v4, 14, v28
	v_and_b32_e32 v4, 0xffff8000, v4
	s_waitcnt vmcnt(6)
	v_lshl_add_u32 v4, v29, 11, v4
	v_and_b32_e32 v5, 1, v28
	v_bitop3_b32 v8, v6, s15, v7 bitop3:0xde
	s_cmpk_lt_u32 s14, 0x100
	v_lshl_or_b32 v4, v5, 6, v4
	v_readlane_b32 s6, v252, 56
	v_bitop3_b32 v142, v6, s16, v7 bitop3:0xde
	s_cselect_b64 s[10:11], -1, 0
	v_lshl_add_u32 v138, v30, 1, v4
	v_mov_b32_e32 v139, v181
	s_mov_b32 s59, 0
	v_add_u32_e32 v145, 0, v8
	s_mov_b32 s64, s6
	v_readlane_b32 s65, v252, 53
	s_barrier
	v_readlane_b32 s7, v252, 57
	s_branch .LBB0_38

.LBB0_72:
	s_and_b32 s26, s6, 3
	s_add_i32 m0, s49, 0x18000
	v_lshl_add_u64 v[4:5], v[26:27], 0, s[94:95]
	s_lshl_b32 s6, s7, 13
	s_lshl_b32 s17, s26, 12
	s_nop 0
	s_nop 0
	global_load_lds_dwordx4 v[4:5], off
	v_lshl_add_u64 v[4:5], v[24:25], 0, s[94:95]
	s_add_i32 m0, s49, 0x1a000
	s_add_i32 s64, s49, 0x8000
	s_add_i32 s65, s49, 0xa000
	global_load_lds_dwordx4 v[4:5], off
	v_lshl_add_u64 v[4:5], v[22:23], 0, s[94:95]
	s_mov_b32 m0, s64
	s_add_u32 s18, s10, 0x40080
	global_load_lds_dwordx4 v[4:5], off
	v_lshl_add_u64 v[4:5], v[20:21], 0, s[94:95]
	s_mov_b32 m0, s65
	s_addc_u32 s19, s11, 0
	global_load_lds_dwordx4 v[4:5], off
	s_add_i32 m0, s49, 0x1c000
	v_lshl_add_u64 v[4:5], s[18:19], 0, v[180:181]
	global_load_lds_dwordx4 v[4:5], off
	v_lshl_add_u64 v[4:5], s[18:19], 0, v[150:151]
	s_add_i32 m0, s49, 0x1e000
	v_lshlrev_b32_e32 v9, 2, v28
	global_load_lds_dwordx4 v[4:5], off
	s_waitcnt vmcnt(8)
	s_barrier
	v_bfe_u32 v5, v28, 4, 2
	v_and_b32_e32 v4, 15, v28
	v_lshlrev_b32_e32 v7, 4, v5
	v_lshl_or_b32 v3, s7, 6, v4
	v_lshl_or_b32 v4, v4, 6, v7
	v_and_b32_e32 v9, 32, v9
	s_cmpk_lt_u32 s16, 0x100
	v_readlane_b32 s72, v251, 4
	v_lshlrev_b32_e32 v7, 2, v3
	v_bitop3_b32 v159, v4, s17, v9 bitop3:0xde
	s_cselect_b64 s[16:17], -1, 0
	s_lshl_b32 s18, s26, 7
	v_readlane_b32 s74, v251, 6
	v_and_b32_e32 v8, 32, v7
	v_readlane_b32 s75, v251, 7
	s_add_u32 s18, s74, s18
	v_lshlrev_b32_e32 v6, 3, v5
	v_bitop3_b32 v8, v4, s6, v8 bitop3:0xde
	v_cmp_eq_u32_e64 s[6:7], 0, v5
	s_addc_u32 s19, s75, 0
	v_lshlrev_b32_e32 v4, 5, v5
	v_mov_b32_e32 v5, v181
	v_lshl_add_u64 v[152:153], s[18:19], 0, v[4:5]
	v_lshlrev_b32_e32 v4, 14, v29
	v_and_b32_e32 v4, 0xffff8000, v4
	v_lshl_add_u32 v4, v30, 11, v4
	v_and_b32_e32 v5, 1, v29
	v_lshl_or_b32 v4, v5, 6, v4
	v_lshl_add_u32 v154, v31, 1, v4
	v_lshlrev_b32_e32 v4, 14, v32
	v_and_b32_e32 v4, 0xffff8000, v4
	s_waitcnt vmcnt(6)
	v_readlane_b32 s84, v251, 16
	v_readlane_b32 s85, v251, 17
	v_readlane_b32 s86, v251, 18
	v_readlane_b32 s87, v251, 19
	s_lshl_b32 s18, s26, 2
	v_lshl_add_u32 v4, v33, 11, v4
	v_and_b32_e32 v5, 1, v32
	v_lshlrev_b32_e32 v161, 4, v3
	s_add_i32 s88, s18, 0
	s_add_i32 s18, 0, 0x22000
	v_lshl_or_b32 v4, v5, 6, v4
	v_readlane_b32 s84, v254, 37
	v_readlane_b32 s86, v254, 39
	s_mov_b32 s68, 0
	v_or_b32_e32 v163, 0x100, v161
	v_or_b32_e32 v165, 0x200, v161
	v_or_b32_e32 v167, 0x300, v161
	v_add_u32_e32 v169, 0x800, v161
	v_add_u32_e32 v171, 0x900, v161
	v_add_u32_e32 v173, 0xa00, v161
	v_add_u32_e32 v176, 0xb00, v161
	s_ashr_i32 s69, s54, 31
	s_add_i32 s88, s88, 0x20000
	v_lshl_or_b32 v177, s26, 5, v6
	v_add_u32_e32 v178, s18, v7
	v_mov_b32_e32 v155, v181
	v_lshl_add_u32 v156, v34, 1, v4
	v_mov_b32_e32 v157, v181
	v_add_u32_e32 v179, 0, v8
	v_readlane_b32 s85, v254, 38
	v_readlane_b32 s87, v254, 40
	s_barrier
	v_readlane_b32 s73, v251, 5
	v_readlane_b32 s76, v251, 8
	v_readlane_b32 s77, v251, 9
	v_readlane_b32 s78, v251, 10
	v_readlane_b32 s79, v251, 11
	v_readlane_b32 s80, v251, 12
	v_readlane_b32 s81, v251, 13
	v_readlane_b32 s82, v251, 14
	v_readlane_b32 s83, v251, 15
	s_branch .LBB0_75

.LBB0_136:
	v_readlane_b32 s44, v253, 10
	v_readlane_b32 s45, v253, 11
	v_mov_b32_e32 v135, v181
	v_readlane_b32 s36, v253, 6
	v_lshl_add_u64 v[4:5], s[44:45], 0, v[180:181]
	v_lshl_add_u64 v[6:7], s[44:45], 0, v[134:135]
	v_mov_b32_e32 v1, v181
	v_readlane_b32 s37, v253, 7
	s_add_i32 m0, s49, 0x18000
	v_lshl_add_u64 v[4:5], v[4:5], 0, s[94:95]
	v_lshl_add_u64 v[8:9], s[36:37], 0, v[0:1]
	v_mov_b32_e32 v133, v181
	s_nop 0
	s_nop 0
	global_load_lds_dwordx4 v[4:5], off
	v_lshl_add_u64 v[4:5], v[6:7], 0, s[94:95]
	s_add_i32 m0, s49, 0x1a000
	s_add_i32 s53, s49, 0x8000
	v_lshl_add_u64 v[10:11], s[36:37], 0, v[132:133]
	global_load_lds_dwordx4 v[4:5], off
	v_lshl_add_u64 v[4:5], v[8:9], 0, s[94:95]
	s_mov_b32 m0, s53
	s_add_i32 s54, s49, 0xa000
	v_readlane_b32 s14, v253, 12
	global_load_lds_dwordx4 v[4:5], off
	v_lshl_add_u64 v[4:5], v[10:11], 0, s[94:95]
	s_mov_b32 m0, s54
	v_readlane_b32 s15, v253, 13
	global_load_lds_dwordx4 v[4:5], off
	s_add_i32 m0, s49, 0x1c000
	v_lshl_add_u64 v[4:5], s[14:15], 0, v[180:181]
	global_load_lds_dwordx4 v[4:5], off
	v_lshl_add_u64 v[4:5], s[14:15], 0, v[134:135]
	s_add_i32 m0, s49, 0x1e000
	v_lshrrev_b32_e32 v13, 1, v21
	global_load_lds_dwordx4 v[4:5], off
	s_waitcnt vmcnt(8)
	s_barrier
	v_lshlrev_b32_e32 v4, 14, v20
	v_and_b32_e32 v4, 0xffff8000, v4
	v_and_b32_e32 v13, 24, v13
	v_lshl_add_u32 v4, v22, 11, v4
	v_and_b32_e32 v5, 1, v20
	v_and_b32_e32 v12, 15, v21
	v_lshlrev_b32_e32 v14, 1, v13
	v_lshl_or_b32 v4, v5, 6, v4
	v_lshl_or_b32 v3, s6, 6, v12
	v_lshl_or_b32 v14, v12, 6, v14
	s_lshl_b32 s13, s6, 13
	v_lshlrev_b32_e32 v12, 2, v12
	s_lshl_b32 s7, s7, 5
	s_lshl_b32 s6, s6, 8
	v_lshl_add_u32 v136, v23, 1, v4
	v_lshlrev_b32_e32 v4, 14, v24
	v_and_b32_e32 v15, 32, v12
	s_and_b32 s7, s7, 0x60
	s_add_i32 s6, s6, 0
	v_and_b32_e32 v4, 0xffff8000, v4
	v_bitop3_b32 v16, v14, s13, v15 bitop3:0xde
	s_lshl_b32 s13, s7, 7
	s_waitcnt vmcnt(6)
	s_add_i32 s6, s6, 0x22000
	v_lshl_add_u32 v4, v25, 11, v4
	v_and_b32_e32 v5, 1, v24
	v_add_u32_e32 v141, s6, v12
	s_cmpk_lt_u32 s12, 0x100
	v_or_b32_e32 v142, s7, v13
	v_lshl_or_b32 v4, v5, 6, v4
	v_readlane_b32 s6, v253, 0
	v_bitop3_b32 v140, v14, s13, v15 bitop3:0xde
	s_cselect_b64 s[12:13], -1, 0
	v_mov_b32_e32 v137, v181
	v_lshl_add_u32 v138, v26, 1, v4
	v_mov_b32_e32 v139, v181
	s_mov_b32 s55, 0
	v_add_u32_e32 v143, 0, v16
	s_mov_b32 s58, s6
	v_readlane_b32 s59, v252, 63
	s_barrier
	v_readlane_b32 s7, v253, 1
	s_branch .LBB0_139

.LBB0_169:
	s_nop 0
	v_bfe_u32 v20, v10, 4, 2
	v_readlane_b32 s46, v253, 43
	v_and_b32_e32 v11, 15, v10
	v_lshlrev_b32_e32 v22, 4, v20
	v_lshlrev_b32_e32 v10, 2, v10
	v_mov_b32_e32 v163, v181
	v_readlane_b32 s47, v253, 44
	s_and_b32 s9, s7, 3
	v_lshl_or_b32 v3, s8, 6, v11
	v_lshl_or_b32 v11, v11, 6, v22
	s_lshl_b32 s7, s8, 13
	v_and_b32_e32 v10, 32, v10
	v_lshl_add_u64 v[12:13], s[46:47], 0, v[162:163]
	v_mov_b32_e32 v1, v181
	v_readlane_b32 s48, v253, 39
	v_bitop3_b32 v22, v11, s7, v10 bitop3:0xde
	s_lshl_b32 s7, s9, 12
	v_lshl_add_u64 v[14:15], s[46:47], 0, v[0:1]
	v_mov_b32_e32 v165, v181
	v_readlane_b32 s49, v253, 40
	v_bitop3_b32 v187, v11, s7, v10 bitop3:0xde
	s_add_i32 m0, s51, 0x18000
	v_lshl_add_u64 v[10:11], v[12:13], 0, s[94:95]
	v_lshl_add_u64 v[16:17], s[48:49], 0, v[164:165]
	v_mov_b32_e32 v161, v181
	s_nop 0
	s_nop 0
	global_load_lds_dwordx4 v[10:11], off
	v_lshl_add_u64 v[10:11], v[14:15], 0, s[94:95]
	s_add_i32 m0, s51, 0x1a000
	s_add_i32 s55, s51, 0x8000
	v_lshl_add_u64 v[18:19], s[48:49], 0, v[160:161]
	global_load_lds_dwordx4 v[10:11], off
	v_lshl_add_u64 v[10:11], v[16:17], 0, s[94:95]
	s_mov_b32 m0, s55
	s_add_i32 s58, s51, 0xa000
	v_readlane_b32 s10, v253, 45
	global_load_lds_dwordx4 v[10:11], off
	v_lshl_add_u64 v[10:11], v[18:19], 0, s[94:95]
	s_mov_b32 m0, s58
	v_readlane_b32 s11, v253, 46
	global_load_lds_dwordx4 v[10:11], off
	s_add_i32 m0, s51, 0x1c000
	v_lshl_add_u64 v[10:11], s[10:11], 0, v[162:163]
	global_load_lds_dwordx4 v[10:11], off
	v_lshl_add_u64 v[10:11], s[10:11], 0, v[0:1]
	s_add_i32 m0, s51, 0x1e000
	s_cmpk_lt_u32 s6, 0x100
	global_load_lds_dwordx4 v[10:11], off
	s_waitcnt vmcnt(8)
	s_barrier
	v_lshlrev_b32_e32 v10, 14, v8
	v_and_b32_e32 v10, 0xffff8000, v10
	v_lshl_add_u32 v7, v7, 11, v10
	v_and_b32_e32 v8, 1, v8
	s_cselect_b64 s[14:15], -1, 0
	s_lshl_b32 s8, s9, 2
	v_lshl_or_b32 v7, v8, 6, v7
	s_add_i32 s8, s8, 0
	v_lshl_add_u32 v166, v9, 1, v7
	v_lshlrev_b32_e32 v7, 14, v4
	v_lshlrev_b32_e32 v21, 3, v20
	s_add_i32 s8, s8, 0x20000
	v_and_b32_e32 v7, 0xffff8000, v7
	s_waitcnt vmcnt(6)
	v_lshl_or_b32 v192, s9, 5, v21
	v_lshl_add_u32 v193, v3, 4, s8
	v_lshl_add_u32 v5, v5, 11, v7
	v_and_b32_e32 v4, 1, v4
	v_readlane_b32 s8, v253, 19
	v_lshl_or_b32 v4, v4, 6, v5
	s_mov_b32 s17, s8
	v_readlane_b32 s8, v254, 12
	s_mov_b32 s59, 0
	v_cmp_eq_u32_e64 s[6:7], 0, v20
	v_mov_b32_e32 v167, v181
	v_lshl_add_u32 v168, v6, 1, v4
	v_mov_b32_e32 v169, v181
	v_add_u32_e32 v194, 0, v22
	s_mov_b32 s16, s8
	s_barrier
	v_readlane_b32 s9, v253, 20
	s_branch .LBB0_172

.LBB0_221:
	v_readlane_b32 s12, v253, 29
	v_readlane_b32 s13, v253, 30
	v_mov_b32_e32 v151, v181
	v_readlane_b32 s36, v253, 25
	v_lshl_add_u64 v[4:5], s[12:13], 0, v[180:181]
	v_lshl_add_u64 v[6:7], s[12:13], 0, v[150:151]
	v_mov_b32_e32 v1, v181
	v_readlane_b32 s37, v253, 26
	s_add_i32 m0, s49, 0x18000
	v_lshl_add_u64 v[4:5], v[4:5], 0, s[94:95]
	v_lshl_add_u64 v[8:9], s[36:37], 0, v[0:1]
	v_mov_b32_e32 v149, v181
	s_nop 0
	s_nop 0
	global_load_lds_dwordx4 v[4:5], off
	v_lshl_add_u64 v[4:5], v[6:7], 0, s[94:95]
	s_add_i32 m0, s49, 0x1a000
	s_add_i32 s55, s49, 0x8000
	v_lshl_add_u64 v[10:11], s[36:37], 0, v[148:149]
	global_load_lds_dwordx4 v[4:5], off
	v_lshl_add_u64 v[4:5], v[8:9], 0, s[94:95]
	s_mov_b32 m0, s55
	s_add_i32 s58, s49, 0xa000
	v_readlane_b32 s10, v253, 31
	global_load_lds_dwordx4 v[4:5], off
	v_lshl_add_u64 v[4:5], v[10:11], 0, s[94:95]
	s_mov_b32 m0, s58
	v_readlane_b32 s11, v253, 32
	global_load_lds_dwordx4 v[4:5], off
	s_add_i32 m0, s49, 0x1c000
	v_lshl_add_u64 v[4:5], s[10:11], 0, v[180:181]
	global_load_lds_dwordx4 v[4:5], off
	v_lshl_add_u64 v[4:5], s[10:11], 0, v[150:151]
	s_add_i32 m0, s49, 0x1e000
	s_and_b32 s10, s6, 3
	global_load_lds_dwordx4 v[4:5], off
	s_waitcnt vmcnt(8)
	s_barrier
	v_and_b32_e32 v4, 15, v20
	v_bfe_u32 v5, v20, 4, 2
	v_lshl_or_b32 v3, s7, 6, v4
	v_lshlrev_b32_e32 v7, 4, v5
	v_lshl_or_b32 v4, v4, 6, v7
	v_lshlrev_b32_e32 v7, 2, v3
	s_lshl_b32 s6, s7, 13
	v_and_b32_e32 v8, 32, v7
	v_bitop3_b32 v8, v4, s6, v8 bitop3:0xde
	s_lshl_b32 s6, s10, 12
	s_cmpk_lt_u32 s8, 0x100
	s_cselect_b64 s[16:17], -1, 0
	s_lshl_b32 s8, s10, 2
	s_add_i32 s64, s8, 0
	v_lshlrev_b32_e32 v9, 2, v20
	s_add_i32 s64, s64, 0x20000
	s_lshl_b32 s8, s10, 7
	v_and_b32_e32 v9, 32, v9
	s_add_u32 s8, s71, s8
	v_lshlrev_b32_e32 v6, 3, v5
	v_bitop3_b32 v159, v4, s6, v9 bitop3:0xde
	v_cmp_eq_u32_e64 s[6:7], 0, v5
	s_addc_u32 s9, s72, 0
	v_lshlrev_b32_e32 v4, 5, v5
	v_mov_b32_e32 v5, v181
	v_lshl_add_u64 v[152:153], s[8:9], 0, v[4:5]
	v_lshlrev_b32_e32 v4, 14, v21
	v_and_b32_e32 v4, 0xffff8000, v4
	v_lshl_add_u32 v4, v22, 11, v4
	v_and_b32_e32 v5, 1, v21
	v_lshl_or_b32 v4, v5, 6, v4
	v_lshl_add_u32 v154, v23, 1, v4
	v_lshlrev_b32_e32 v4, 14, v24
	v_and_b32_e32 v4, 0xffff8000, v4
	s_waitcnt vmcnt(6)
	s_add_i32 s8, 0, 0x22000
	v_lshl_add_u32 v4, v25, 11, v4
	v_and_b32_e32 v5, 1, v24
	v_lshlrev_b32_e32 v161, 4, v3
	v_add_u32_e32 v178, s8, v7
	v_lshl_or_b32 v4, v5, 6, v4
	v_readlane_b32 s8, v253, 19
	s_mov_b32 s59, 0
	v_or_b32_e32 v189, 0x100, v161
	v_or_b32_e32 v165, 0x200, v161
	v_or_b32_e32 v167, 0x300, v161
	v_add_u32_e32 v169, 0x800, v161
	v_add_u32_e32 v171, 0x900, v161
	v_add_u32_e32 v173, 0xa00, v161
	v_add_u32_e32 v176, 0xb00, v161
	v_lshl_or_b32 v177, s10, 5, v6
	v_mov_b32_e32 v155, v181
	v_lshl_add_u32 v156, v26, 1, v4
	v_mov_b32_e32 v157, v181
	v_add_u32_e32 v179, 0, v8
	s_mov_b32 s65, s8
	v_readlane_b32 s68, v254, 12
	s_mov_b64 s[10:11], s[36:37]
	s_barrier
	v_readlane_b32 s9, v253, 20
	s_branch .LBB0_224

.LBB0_285:
	v_readlane_b32 s44, v253, 29
	v_readlane_b32 s45, v253, 30
	v_mov_b32_e32 v135, v181
	v_readlane_b32 s36, v253, 25
	v_lshl_add_u64 v[4:5], s[44:45], 0, v[180:181]
	v_lshl_add_u64 v[6:7], s[44:45], 0, v[134:135]
	v_mov_b32_e32 v1, v181
	v_readlane_b32 s37, v253, 26
	s_add_i32 m0, s59, 0x18000
	v_lshl_add_u64 v[4:5], v[4:5], 0, s[94:95]
	v_lshl_add_u64 v[8:9], s[36:37], 0, v[0:1]
	v_mov_b32_e32 v133, v181
	s_nop 0
	s_nop 0
	global_load_lds_dwordx4 v[4:5], off
	v_lshl_add_u64 v[4:5], v[6:7], 0, s[94:95]
	s_add_i32 m0, s59, 0x1a000
	s_add_i32 s69, s59, 0x8000
	v_lshl_add_u64 v[10:11], s[36:37], 0, v[132:133]
	global_load_lds_dwordx4 v[4:5], off
	v_lshl_add_u64 v[4:5], v[8:9], 0, s[94:95]
	s_mov_b32 m0, s69
	s_add_i32 s88, s59, 0xa000
	v_readlane_b32 s12, v253, 31
	global_load_lds_dwordx4 v[4:5], off
	v_lshl_add_u64 v[4:5], v[10:11], 0, s[94:95]
	s_mov_b32 m0, s88
	v_readlane_b32 s13, v253, 32
	global_load_lds_dwordx4 v[4:5], off
	s_add_i32 m0, s59, 0x1c000
	v_lshl_add_u64 v[4:5], s[12:13], 0, v[180:181]
	global_load_lds_dwordx4 v[4:5], off
	v_lshl_add_u64 v[4:5], s[12:13], 0, v[134:135]
	s_add_i32 m0, s59, 0x1e000
	v_bfe_u32 v144, v20, 4, 2
	global_load_lds_dwordx4 v[4:5], off
	s_waitcnt vmcnt(8)
	s_barrier
	v_and_b32_e32 v3, 15, v20
	v_lshlrev_b32_e32 v151, 4, v144
	v_lshlrev_b32_e32 v5, 2, v20
	s_and_b32 s52, s6, 3
	v_lshl_or_b32 v4, v3, 6, v151
	s_lshl_b32 s6, s55, 13
	v_and_b32_e32 v5, 32, v5
	v_bitop3_b32 v6, v4, s6, v5 bitop3:0xde
	s_lshl_b32 s6, s52, 12
	v_bitop3_b32 v145, v4, s6, v5 bitop3:0xde
	v_lshlrev_b32_e32 v4, 14, v21
	v_and_b32_e32 v4, 0xffff8000, v4
	v_lshl_add_u32 v4, v22, 11, v4
	v_and_b32_e32 v5, 1, v21
	v_lshl_or_b32 v4, v5, 6, v4
	v_lshl_add_u32 v136, v23, 1, v4
	v_lshlrev_b32_e32 v4, 14, v24
	v_and_b32_e32 v4, 0xffff8000, v4
	v_lshl_add_u32 v4, v25, 11, v4
	v_and_b32_e32 v5, 1, v24
	s_waitcnt vmcnt(6)
	v_lshl_or_b32 v4, v5, 6, v4
	v_mov_b32_e32 v32, v181
	v_mov_b32_e32 v33, v181
	v_mov_b32_e32 v34, v181
	v_mov_b32_e32 v35, v181
	s_cmpk_lt_u32 s8, 0x100
	v_lshl_add_u32 v138, v26, 1, v4
	v_add_u32_e32 v146, 0, v6
	v_mov_b64_e32 v[38:39], v[34:35]
	v_mov_b64_e32 v[24:25], v[32:33]
	v_mov_b64_e32 v[28:29], v[32:33]
	v_mov_b64_e32 v[16:17], v[32:33]
	v_mov_b64_e32 v[20:21], v[32:33]
	v_mov_b64_e32 v[8:9], v[32:33]
	v_mov_b64_e32 v[12:13], v[32:33]
	v_mov_b64_e32 v[42:43], v[34:35]
	v_mov_b64_e32 v[46:47], v[34:35]
	v_mov_b64_e32 v[50:51], v[34:35]
	v_mov_b64_e32 v[54:55], v[34:35]
	v_mov_b64_e32 v[58:59], v[34:35]
	v_mov_b64_e32 v[62:63], v[34:35]
	v_mov_b64_e32 v[4:5], v[32:33]
	v_mov_b64_e32 v[66:67], v[34:35]
	v_mov_b64_e32 v[70:71], v[34:35]
	v_mov_b64_e32 v[74:75], v[34:35]
	v_mov_b64_e32 v[78:79], v[34:35]
	v_mov_b64_e32 v[86:87], v[34:35]
	v_mov_b64_e32 v[94:95], v[34:35]
	v_mov_b64_e32 v[102:103], v[34:35]
	v_mov_b64_e32 v[118:119], v[34:35]
	v_mov_b64_e32 v[122:123], v[34:35]
	v_mov_b64_e32 v[82:83], v[34:35]
	v_mov_b64_e32 v[90:91], v[34:35]
	v_mov_b64_e32 v[98:99], v[34:35]
	v_mov_b64_e32 v[106:107], v[34:35]
	v_mov_b64_e32 v[110:111], v[34:35]
	v_mov_b64_e32 v[114:115], v[34:35]
	v_mov_b64_e32 v[126:127], v[34:35]
	v_mov_b64_e32 v[130:131], v[34:35]
	v_readlane_b32 s6, v253, 19
	v_lshl_or_b32 v149, s55, 6, v3
	s_cselect_b64 s[12:13], -1, 0
	v_mov_b32_e32 v137, v181
	v_mov_b32_e32 v139, v181
	s_mov_b32 s90, 0
	v_mov_b64_e32 v[36:37], v[32:33]
	v_mov_b64_e32 v[26:27], v[34:35]
	v_mov_b64_e32 v[30:31], v[34:35]
	v_mov_b64_e32 v[18:19], v[34:35]
	v_mov_b64_e32 v[22:23], v[34:35]
	v_mov_b64_e32 v[10:11], v[34:35]
	v_mov_b64_e32 v[14:15], v[34:35]
	v_mov_b64_e32 v[40:41], v[32:33]
	v_mov_b64_e32 v[44:45], v[32:33]
	v_mov_b64_e32 v[48:49], v[32:33]
	v_mov_b64_e32 v[52:53], v[32:33]
	v_mov_b64_e32 v[56:57], v[32:33]
	v_mov_b64_e32 v[60:61], v[32:33]
	v_mov_b64_e32 v[6:7], v[34:35]
	v_mov_b64_e32 v[64:65], v[32:33]
	v_mov_b64_e32 v[68:69], v[32:33]
	v_mov_b64_e32 v[72:73], v[32:33]
	v_mov_b64_e32 v[76:77], v[32:33]
	v_mov_b64_e32 v[84:85], v[32:33]
	v_mov_b64_e32 v[92:93], v[32:33]
	v_mov_b64_e32 v[100:101], v[32:33]
	v_mov_b64_e32 v[116:117], v[32:33]
	v_mov_b64_e32 v[120:121], v[32:33]
	v_mov_b64_e32 v[80:81], v[32:33]
	v_mov_b64_e32 v[88:89], v[32:33]
	v_mov_b64_e32 v[96:97], v[32:33]
	v_mov_b64_e32 v[104:105], v[32:33]
	v_mov_b64_e32 v[108:109], v[32:33]
	v_mov_b64_e32 v[112:113], v[32:33]
	v_mov_b64_e32 v[124:125], v[32:33]
	v_mov_b64_e32 v[128:129], v[32:33]
	s_mov_b32 s54, s6
	v_readlane_b32 s53, v254, 12
	s_barrier
	v_readlane_b32 s7, v253, 20

.LBB0_324:
	s_nop 0
	v_bfe_u32 v20, v10, 4, 2
	v_readlane_b32 s46, v253, 55
	v_and_b32_e32 v11, 15, v10
	v_lshlrev_b32_e32 v22, 4, v20
	v_lshlrev_b32_e32 v10, 2, v10
	v_mov_b32_e32 v163, v181
	v_readlane_b32 s47, v253, 56
	s_and_b32 s9, s7, 3
	v_lshl_or_b32 v3, s8, 6, v11
	v_lshl_or_b32 v11, v11, 6, v22
	s_lshl_b32 s7, s8, 13
	v_and_b32_e32 v10, 32, v10
	v_lshl_add_u64 v[12:13], s[46:47], 0, v[162:163]
	v_mov_b32_e32 v1, v181
	v_readlane_b32 s44, v253, 51
	v_bitop3_b32 v22, v11, s7, v10 bitop3:0xde
	s_lshl_b32 s7, s9, 12
	v_lshl_add_u64 v[14:15], s[46:47], 0, v[0:1]
	v_mov_b32_e32 v165, v181
	v_readlane_b32 s45, v253, 52
	v_bitop3_b32 v187, v11, s7, v10 bitop3:0xde
	s_add_i32 m0, s51, 0x18000
	v_lshl_add_u64 v[10:11], v[12:13], 0, s[94:95]
	v_lshl_add_u64 v[16:17], s[44:45], 0, v[164:165]
	v_mov_b32_e32 v161, v181
	s_nop 0
	s_nop 0
	global_load_lds_dwordx4 v[10:11], off
	v_lshl_add_u64 v[10:11], v[14:15], 0, s[94:95]
	s_add_i32 m0, s51, 0x1a000
	s_add_i32 s55, s51, 0x8000
	v_lshl_add_u64 v[18:19], s[44:45], 0, v[160:161]
	global_load_lds_dwordx4 v[10:11], off
	v_lshl_add_u64 v[10:11], v[16:17], 0, s[94:95]
	s_mov_b32 m0, s55
	s_add_i32 s58, s51, 0xa000
	v_readlane_b32 s12, v253, 57
	global_load_lds_dwordx4 v[10:11], off
	v_lshl_add_u64 v[10:11], v[18:19], 0, s[94:95]
	s_mov_b32 m0, s58
	v_readlane_b32 s13, v253, 58
	global_load_lds_dwordx4 v[10:11], off
	s_add_i32 m0, s51, 0x1c000
	v_lshl_add_u64 v[10:11], s[12:13], 0, v[162:163]
	global_load_lds_dwordx4 v[10:11], off
	v_lshl_add_u64 v[10:11], s[12:13], 0, v[0:1]
	s_add_i32 m0, s51, 0x1e000
	s_cmpk_lt_u32 s6, 0x100
	global_load_lds_dwordx4 v[10:11], off
	s_waitcnt vmcnt(8)
	s_barrier
	v_lshlrev_b32_e32 v10, 14, v8
	v_and_b32_e32 v10, 0xffff8000, v10
	v_lshl_add_u32 v7, v7, 11, v10
	v_and_b32_e32 v8, 1, v8
	s_cselect_b64 s[12:13], -1, 0
	s_lshl_b32 s8, s9, 2
	v_lshl_or_b32 v7, v8, 6, v7
	s_add_i32 s8, s8, 0
	v_lshl_add_u32 v166, v9, 1, v7
	v_lshlrev_b32_e32 v7, 14, v4
	v_lshlrev_b32_e32 v21, 3, v20
	s_add_i32 s8, s8, 0x20000
	v_and_b32_e32 v7, 0xffff8000, v7
	s_waitcnt vmcnt(6)
	v_lshl_or_b32 v192, s9, 5, v21
	v_lshl_add_u32 v193, v3, 4, s8
	v_lshl_add_u32 v5, v5, 11, v7
	v_and_b32_e32 v4, 1, v4
	v_readlane_b32 s8, v253, 19
	v_lshl_or_b32 v4, v4, 6, v5
	s_mov_b32 s15, s8
	v_readlane_b32 s8, v254, 12
	s_mov_b32 s59, 0
	v_cmp_eq_u32_e64 s[6:7], 0, v20
	v_mov_b32_e32 v167, v181
	v_lshl_add_u32 v168, v6, 1, v4
	v_mov_b32_e32 v169, v181
	v_add_u32_e32 v194, 0, v22
	s_mov_b32 s14, s8
	s_barrier
	v_readlane_b32 s9, v253, 20
	s_branch .LBB0_327

.LBB0_581:
	v_lshrrev_b32_e32 v22, 1, v16
	v_and_b32_e32 v22, 24, v22
	v_readlane_b32 s26, v253, 14
	v_and_b32_e32 v17, 15, v16
	v_lshlrev_b32_e32 v23, 1, v22
	v_lshlrev_b32_e32 v16, 2, v16
	s_lshl_b32 s7, s7, 5
	v_mov_b32_e32 v155, v181
	v_readlane_b32 s27, v253, 15
	v_lshl_or_b32 v3, s8, 6, v17
	v_lshl_or_b32 v17, v17, 6, v23
	s_lshl_b32 s8, s8, 13
	v_and_b32_e32 v16, 32, v16
	s_and_b32 s7, s7, 0x60
	s_add_i32 m0, s49, 0x18000
	v_lshl_add_u64 v[4:5], v[4:5], 0, s[94:95]
	v_lshl_add_u64 v[18:19], s[26:27], 0, v[154:155]
	v_mov_b32_e32 v153, v181
	v_bitop3_b32 v23, v17, s8, v16 bitop3:0xde
	s_lshl_b32 s8, s7, 7
	s_nop 0
	s_nop 0
	global_load_lds_dwordx4 v[4:5], off
	v_lshl_add_u64 v[4:5], v[6:7], 0, s[94:95]
	s_add_i32 m0, s49, 0x1a000
	s_add_i32 s54, s49, 0x8000
	s_add_i32 s55, s49, 0xa000
	v_lshl_add_u64 v[20:21], s[26:27], 0, v[152:153]
	v_bitop3_b32 v170, v17, s8, v16 bitop3:0xde
	global_load_lds_dwordx4 v[4:5], off
	v_lshl_add_u64 v[4:5], v[18:19], 0, s[94:95]
	s_mov_b32 m0, s54
	s_add_u32 s8, s36, 0xb0080
	global_load_lds_dwordx4 v[4:5], off
	v_lshl_add_u64 v[4:5], v[20:21], 0, s[94:95]
	s_mov_b32 m0, s55
	s_addc_u32 s9, s37, 0
	global_load_lds_dwordx4 v[4:5], off
	s_add_i32 m0, s49, 0x1c000
	v_lshl_add_u64 v[4:5], s[8:9], 0, v[180:181]
	global_load_lds_dwordx4 v[4:5], off
	v_lshl_add_u64 v[4:5], s[8:9], 0, v[0:1]
	s_add_i32 m0, s49, 0x1e000
	s_movk_i32 s8, 0xb00
	global_load_lds_dwordx4 v[4:5], off
	s_waitcnt vmcnt(8)
	s_barrier
	v_lshrrev_b32_e32 v5, 1, v13
	v_mul_lo_u32 v4, v12, s8
	s_mov_b32 s9, 0xb000
	s_cmpk_lt_u32 s6, 0x100
	v_or_b32_e32 v171, s7, v22
	v_mad_u64_u32 v[4:5], s[6:7], v5, s9, v[4:5]
	v_or_b32_e32 v4, v4, v14
	v_add_lshl_u32 v4, v4, v15, 1
	v_mov_b32_e32 v5, v181
	s_mov_b64 s[18:19], 0xb0080
	v_lshl_add_u64 v[156:157], v[4:5], 0, s[18:19]
	v_lshrrev_b32_e32 v5, 1, v8
	v_mul_lo_u32 v4, v9, s8
	v_mad_u64_u32 v[4:5], s[6:7], v5, s9, v[4:5]
	s_waitcnt vmcnt(6)
	v_or_b32_e32 v4, v4, v10
	v_add_lshl_u32 v4, v4, v11, 1
	v_mov_b32_e32 v5, v181
	v_readlane_b32 s6, v253, 19
	s_cselect_b64 s[16:17], -1, 0
	v_lshl_add_u64 v[158:159], v[4:5], 0, s[18:19]
	s_mov_b32 s58, 0
	v_add_u32_e32 v172, 0, v23
	s_mov_b32 s65, s6
	v_readlane_b32 s68, v254, 12
	s_barrier
	v_readlane_b32 s7, v253, 20
	s_branch .LBB0_584

.LBB0_610:
	s_and_b64 s[10:11], s[10:11], exec
	s_mov_b32 s10, 0x10000
	s_cselect_b32 s10, 0x50000, s10
	v_readlane_b32 s44, v253, 14
	s_add_u32 s16, s20, s10
	v_mov_b32_e32 v165, v181
	v_readlane_b32 s45, v253, 15
	s_addc_u32 s17, s21, 0
	s_and_b32 s12, s12, 3
	s_add_i32 m0, s54, 0x18000
	v_lshl_add_u64 v[4:5], v[4:5], 0, s[94:95]
	v_lshl_add_u64 v[18:19], s[44:45], 0, v[164:165]
	v_mov_b32_e32 v161, v181
	s_lshl_b32 s13, s9, 13
	s_lshl_b32 s18, s12, 12
	s_nop 0
	s_nop 0
	global_load_lds_dwordx4 v[4:5], off
	v_lshl_add_u64 v[4:5], v[6:7], 0, s[94:95]
	s_add_i32 m0, s54, 0x1a000
	s_add_i32 s64, s54, 0x8000
	s_add_i32 s65, s54, 0xa000
	v_lshl_add_u64 v[20:21], s[44:45], 0, v[160:161]
	global_load_lds_dwordx4 v[4:5], off
	v_lshl_add_u64 v[4:5], v[18:19], 0, s[94:95]
	s_mov_b32 m0, s64
	s_add_u32 s10, s46, 0xb0080
	global_load_lds_dwordx4 v[4:5], off
	v_lshl_add_u64 v[4:5], v[20:21], 0, s[94:95]
	s_mov_b32 m0, s65
	s_addc_u32 s11, s47, 0
	global_load_lds_dwordx4 v[4:5], off
	s_add_i32 m0, s54, 0x1c000
	v_lshl_add_u64 v[4:5], s[10:11], 0, v[162:163]
	global_load_lds_dwordx4 v[4:5], off
	v_lshl_add_u64 v[4:5], s[10:11], 0, v[0:1]
	s_add_i32 m0, s54, 0x1e000
	s_cmpk_lt_u32 s8, 0x100
	global_load_lds_dwordx4 v[4:5], off
	s_waitcnt vmcnt(8)
	s_barrier
	v_bfe_u32 v4, v10, 4, 2
	v_and_b32_e32 v5, 15, v10
	v_lshlrev_b32_e32 v7, 4, v4
	v_lshl_or_b32 v3, s9, 6, v5
	v_lshl_or_b32 v5, v5, 6, v7
	v_lshlrev_b32_e32 v7, 2, v10
	v_and_b32_e32 v7, 32, v7
	v_lshlrev_b32_e32 v6, 3, v4
	v_bitop3_b32 v187, v5, s18, v7 bitop3:0xde
	s_cselect_b64 s[18:19], -1, 0
	s_lshl_b32 s10, s12, 2
	v_lshl_or_b32 v192, s12, 5, v6
	s_add_i32 s10, s10, 0
	s_movk_i32 s12, 0xb00
	v_bitop3_b32 v10, v5, s13, v7 bitop3:0xde
	v_cmp_eq_u32_e64 s[8:9], 0, v4
	s_add_i32 s10, s10, 0x20000
	v_lshrrev_b32_e32 v5, 1, v14
	v_mul_lo_u32 v4, v13, s12
	s_mov_b32 s13, 0xb000
	v_lshl_add_u32 v193, v3, 4, s10
	v_mad_u64_u32 v[4:5], s[10:11], v5, s13, v[4:5]
	v_or_b32_e32 v4, v4, v15
	v_add_lshl_u32 v180, v4, v16, 1
	v_lshrrev_b32_e32 v5, 1, v8
	v_mul_lo_u32 v4, v9, s12
	v_mad_u64_u32 v[4:5], s[10:11], v5, s13, v[4:5]
	s_mov_b64 s[26:27], 0xb0080
	v_or_b32_e32 v4, v4, v11
	s_waitcnt vmcnt(6)
	v_lshl_add_u64 v[166:167], v[180:181], 0, s[26:27]
	v_add_lshl_u32 v180, v4, v12, 1
	v_readlane_b32 s10, v253, 19
	v_lshl_add_u64 v[168:169], v[180:181], 0, s[26:27]
	s_mov_b32 s27, s10
	v_readlane_b32 s10, v254, 12
	s_mov_b32 s68, 0
	v_add_u32_e32 v194, 0, v10
	s_mov_b32 s26, s10
	s_barrier
	v_readlane_b32 s11, v253, 20
	s_branch .LBB0_613

.LBB0_654:
	v_readlane_b32 s26, v253, 14
	v_mov_b32_e32 v195, v181
	v_readlane_b32 s27, v253, 15
	s_and_b32 s9, s7, 3
	s_add_i32 m0, s49, 0x18000
	v_lshl_add_u64 v[4:5], v[4:5], 0, s[94:95]
	v_lshl_add_u64 v[18:19], s[26:27], 0, v[194:195]
	v_mov_b32_e32 v191, v181
	s_lshl_b32 s7, s6, 13
	s_lshl_b32 s14, s9, 12
	s_nop 0
	s_nop 0
	global_load_lds_dwordx4 v[4:5], off
	v_lshl_add_u64 v[4:5], v[6:7], 0, s[94:95]
	s_add_i32 m0, s49, 0x1a000
	s_add_i32 s54, s49, 0x8000
	s_add_i32 s55, s49, 0xa000
	v_lshl_add_u64 v[20:21], s[26:27], 0, v[190:191]
	global_load_lds_dwordx4 v[4:5], off
	v_lshl_add_u64 v[4:5], v[18:19], 0, s[94:95]
	s_mov_b32 m0, s54
	s_add_u32 s10, s36, 0xb0080
	global_load_lds_dwordx4 v[4:5], off
	v_lshl_add_u64 v[4:5], v[20:21], 0, s[94:95]
	s_mov_b32 m0, s55
	s_addc_u32 s11, s37, 0
	global_load_lds_dwordx4 v[4:5], off
	s_add_i32 m0, s49, 0x1c000
	v_lshl_add_u64 v[4:5], s[10:11], 0, v[192:193]
	global_load_lds_dwordx4 v[4:5], off
	v_lshl_add_u64 v[4:5], s[10:11], 0, v[0:1]
	s_add_i32 m0, s49, 0x1e000
	s_cmpk_lt_u32 s8, 0x100
	global_load_lds_dwordx4 v[4:5], off
	s_waitcnt vmcnt(8)
	s_barrier
	v_bfe_u32 v5, v10, 4, 2
	v_and_b32_e32 v4, 15, v10
	v_lshlrev_b32_e32 v7, 4, v5
	v_lshl_or_b32 v3, s6, 6, v4
	v_lshl_or_b32 v4, v4, 6, v7
	v_lshlrev_b32_e32 v7, 2, v10
	v_and_b32_e32 v7, 32, v7
	v_bitop3_b32 v187, v4, s14, v7 bitop3:0xde
	s_cselect_b64 s[14:15], -1, 0
	s_lshl_b32 s8, s9, 2
	s_add_i32 s8, s8, 0
	s_movk_i32 s10, 0xb00
	v_lshlrev_b32_e32 v6, 3, v5
	v_bitop3_b32 v10, v4, s7, v7 bitop3:0xde
	v_cmp_eq_u32_e64 s[6:7], 0, v5
	s_add_i32 s8, s8, 0x20000
	v_lshrrev_b32_e32 v5, 1, v14
	v_mul_lo_u32 v4, v13, s10
	s_mov_b32 s11, 0xb000
	v_lshl_or_b32 v227, s9, 5, v6
	v_lshl_add_u32 v228, v3, 4, s8
	v_mad_u64_u32 v[4:5], s[8:9], v5, s11, v[4:5]
	v_or_b32_e32 v4, v4, v15
	v_add_lshl_u32 v180, v4, v16, 1
	v_lshrrev_b32_e32 v5, 1, v8
	v_mul_lo_u32 v4, v9, s10
	v_mad_u64_u32 v[4:5], s[8:9], v5, s11, v[4:5]
	s_mov_b64 s[16:17], 0xb0080
	v_or_b32_e32 v4, v4, v11
	s_waitcnt vmcnt(6)
	v_lshl_add_u64 v[196:197], v[180:181], 0, s[16:17]
	v_add_lshl_u32 v180, v4, v12, 1
	v_readlane_b32 s8, v253, 19
	v_lshl_add_u64 v[198:199], v[180:181], 0, s[16:17]
	s_mov_b32 s17, s8
	v_readlane_b32 s8, v254, 12
	s_mov_b32 s58, 0
	v_add_u32_e32 v229, 0, v10
	s_mov_b32 s16, s8
	s_barrier
	v_readlane_b32 s9, v253, 20
	s_branch .LBB0_657
